# static s_setprio 1 for waves 4-7 during the mixer phase units (reset at unit end); on top of m13
# speedup vs baseline: 1.0053x; 1.0002x over previous
; #define LAS __attribute__((address_space(3)))
; #define SCHED_FENCE() __builtin_amdgcn_sched_barrier(0)
; #define P5_LAUNDER() int tid = tid_in; asm volatile("" : "+v"(tid)); const int lane = tid & 63, fr = lane & 15, fq = lane >> 4
; __device__ __forceinline__ void p5_unit(const Ptrs& P, LAS unsigned char* lds, int unit, int tid_in, int wave) {
;     ...
;     const int b = unit >> 6, r = unit & 63, tok0 = b * SEQ + r * 64;
;     const int rs = min(max(r - 4, 0), 56);
;     LAS float* rpb = (LAS float*)(lds + RPB_OFF);
;     LAS bf16_t* vvt = (LAS bf16_t*)lds;
;     __syncthreads();
;     {
;         P5_LAUNDER(); (void)fr; (void)fq; (void)lane;
;         float rv[8];
; #pragma unroll
;         for (int k = 0; k < 8; ++k) { const int i = min(tid + 512 * k, 8 * 15 * 32 - 1), c = i & 31; rv[k] = P.in[10][(i >> 5) * 31 + min(c, 30)]; }
;         SCHED_FENCE();
; #pragma unroll
;         for (int k = 0; k < 8; ++k) { const int i = tid + 512 * k; if (i < 8 * 15 * 32) rpb[i] = (i & 31) < 31 ? rv[k] * LOG2E : -1.0e30f; }
; __global__ void __launch_bounds__(512, 2) fwd_kernel(Args a) {
;     ...
;             for (int u = bid; u < 256; u += G) p5_unit(P, lds, (G == 256) ? ((u & 7) * 32 + (u >> 3)) : u, tid, wave);
.LBB0_201:
	s_waitcnt vmcnt(0)
	v_mov_b32_e32 v0, v217
	s_waitcnt vmcnt(0)
	s_barrier
	v_readlane_b32 s0, v253, 4
	s_nop 3
	s_cmp_ge_u32 s0, 32
	s_cbranch_scc0 .Lp5_noprio
	s_setprio 1
.Lp5_noprio:
	v_readlane_b32 s80, v252, 0
	v_min_i32_e32 v1, 0xeff, v0
	v_and_b32_e32 v2, 31, v1
	v_ashrrev_i32_e32 v1, 5, v1
	v_min_u32_e32 v2, 30, v2
	v_mad_u64_u32 v[2:3], s[6:7], v1, 31, v[2:3]
	v_add_u32_e32 v8, 0x200, v0
	v_ashrrev_i32_e32 v3, 31, v2
	v_readlane_b32 s88, v252, 8
	v_readlane_b32 s89, v252, 9
	v_min_i32_e32 v1, 0xeff, v8
	v_add_u32_e32 v6, 0x400, v0
	v_lshl_add_u64 v[10:11], v[2:3], 2, s[88:89]
	v_and_b32_e32 v2, 31, v1
	v_ashrrev_i32_e32 v1, 5, v1
	v_min_u32_e32 v2, 30, v2
	v_mad_u64_u32 v[2:3], s[6:7], v1, 31, v[2:3]
	v_ashrrev_i32_e32 v3, 31, v2
	v_min_i32_e32 v1, 0xeff, v6
	v_lshl_add_u64 v[12:13], v[2:3], 2, s[88:89]
	v_and_b32_e32 v2, 31, v1
	v_ashrrev_i32_e32 v1, 5, v1
	v_min_u32_e32 v2, 30, v2
	v_mad_u64_u32 v[2:3], s[6:7], v1, 31, v[2:3]
	s_waitcnt lgkmcnt(0)
	v_add_u32_e32 v5, 0x600, v0
	v_ashrrev_i32_e32 v3, 31, v2
	v_min_i32_e32 v1, 0xeff, v5
	v_lshl_add_u64 v[16:17], v[2:3], 2, s[88:89]
	v_and_b32_e32 v2, 31, v1
	v_ashrrev_i32_e32 v1, 5, v1
	v_min_u32_e32 v2, 30, v2
	v_mad_u64_u32 v[2:3], s[6:7], v1, 31, v[2:3]
	v_add_u32_e32 v4, 0x800, v0
	v_ashrrev_i32_e32 v3, 31, v2
	v_min_i32_e32 v1, 0xeff, v4
	v_lshl_add_u64 v[18:19], v[2:3], 2, s[88:89]
	v_and_b32_e32 v2, 31, v1
	v_ashrrev_i32_e32 v1, 5, v1
	v_min_u32_e32 v2, 30, v2
	v_mad_u64_u32 v[2:3], s[6:7], v1, 31, v[2:3]
	v_ashrrev_i32_e32 v3, 31, v2
	v_lshl_add_u64 v[20:21], v[2:3], 2, s[88:89]
	v_add_u32_e32 v3, 0xa00, v0
	v_min_i32_e32 v1, 0xeff, v3
	v_and_b32_e32 v2, 31, v1
	v_ashrrev_i32_e32 v1, 5, v1
	v_min_u32_e32 v2, 30, v2
	v_mad_u64_u32 v[14:15], s[6:7], v1, 31, v[2:3]
	v_add_u32_e32 v2, 0xc00, v0
	v_min_i32_e32 v1, 0xeff, v2
	v_ashrrev_i32_e32 v15, 31, v14
	v_and_b32_e32 v7, 31, v1
	v_lshl_add_u64 v[22:23], v[14:15], 2, s[88:89]
	v_ashrrev_i32_e32 v1, 5, v1
	v_min_u32_e32 v14, 30, v7
	v_mad_u64_u32 v[14:15], s[6:7], v1, 31, v[14:15]
	v_add_u32_e32 v1, 0xe00, v0
	v_min_i32_e32 v7, 0xeff, v1
	v_ashrrev_i32_e32 v15, 31, v14
	v_and_b32_e32 v9, 31, v7
	v_lshl_add_u64 v[24:25], v[14:15], 2, s[88:89]
	v_ashrrev_i32_e32 v7, 5, v7
	v_min_u32_e32 v14, 30, v9
	v_mad_u64_u32 v[14:15], s[6:7], v7, 31, v[14:15]
	v_ashrrev_i32_e32 v15, 31, v14
	v_lshl_add_u64 v[26:27], v[14:15], 2, s[88:89]
	global_load_dword v15, v[10:11], off
	global_load_dword v14, v[12:13], off
	s_nop 0
	global_load_dword v13, v[16:17], off
	global_load_dword v12, v[18:19], off
	global_load_dword v11, v[20:21], off
	global_load_dword v10, v[22:23], off
	global_load_dword v9, v[24:25], off
	global_load_dword v7, v[26:27], off
	s_lshl_b32 s6, s12, 5
	s_and_b32 s6, s6, 0xe0
	s_ashr_i32 s7, s12, 3
	v_readlane_b32 s0, v253, 2
	s_add_i32 s8, s6, s7
	v_readlane_b32 s1, v253, 3
	s_and_b64 s[6:7], s[0:1], exec
	s_cselect_b32 s8, s8, s12
	s_and_b32 s18, s8, 63
	v_sub_u32_e64 v16, s18, 4 clamp
	v_readlane_b32 s81, v252, 1
	v_readfirstlane_b32 s19, v16
	v_readlane_b32 s82, v252, 2
	v_readlane_b32 s83, v252, 3
	v_readlane_b32 s84, v252, 4
	v_readlane_b32 s85, v252, 5
	v_readlane_b32 s86, v252, 6
	v_readlane_b32 s87, v252, 7
	v_readlane_b32 s90, v252, 10
	v_readlane_b32 s91, v252, 11
	v_readlane_b32 s92, v252, 12
	v_readlane_b32 s93, v252, 13
	v_readlane_b32 s94, v252, 14
	v_readlane_b32 s95, v252, 15
	v_and_b32_e32 v16, 31, v0
	s_movk_i32 s6, 0xf00
	v_cmp_eq_u32_e32 vcc, 31, v16
	v_cmp_gt_i32_e64 s[38:39], s6, v0
	s_and_saveexec_b64 s[6:7], s[38:39]
	s_cbranch_execz .LBB0_203
	v_lshl_add_u32 v16, v0, 2, 0
	s_waitcnt vmcnt(7)
	v_mul_f32_e32 v15, 0x3fb8aa3b, v15
	v_add_u32_e32 v16, 0x23000, v16
	v_cndmask_b32_e32 v15, v15, v216, vcc
	ds_write_b32 v16, v15

; #define SCHED_FENCE() __builtin_amdgcn_sched_barrier(0)
; __device__ __forceinline__ float bflo(unsigned u) { return __uint_as_float(u << 16); }
; __device__ __forceinline__ float bfhi(unsigned u) { return __uint_as_float(u & 0xffff0000u); }
; __device__ __forceinline__ float shfl_xor_l(float v, int lane, int mask) { return __int_as_float(__builtin_amdgcn_ds_bpermute((lane ^ mask) << 2, __float_as_int(v))); }
; template <int NR>
; __device__ __forceinline__ void rescale_rows(bf16_t* y, size_t stride, const f32x4 (&g0)[4], const f32x4 (&g1)[4], int lane) {
;     u32x4 w[NR][4];
; #pragma unroll
;     for (int i = 0; i < NR; ++i)
; #pragma unroll
;         for (int j = 0; j < 4; ++j) w[i][j] = *(const u32x4*)(y + (size_t)i * stride + 512 * j + 8 * lane);
;     SCHED_FENCE();
;     float sna[NR], ssg[NR], sme[NR];
; #pragma unroll
;     for (int i = 0; i < NR; ++i) {
;         float ss[4];
; #pragma unroll
;         for (int j = 0; j < 4; ++j) { const u32x4 v = w[i][j];
;             const float a0 = bflo(v.x), a1 = bfhi(v.x), a2 = bflo(v.y), a3 = bfhi(v.y), a4 = bflo(v.z), a5 = bfhi(v.z), a6 = bflo(v.w), a7 = bfhi(v.w);
;             ss[j] = (a0 * a0 + a1 * a1) + (a2 * a2 + a3 * a3) + (a4 * a4 + a5 * a5) + (a6 * a6 + a7 * a7); }
;         sna[i] = ss[0] + ss[1]; ssg[i] = ss[2]; sme[i] = ss[3];
;     }
; #pragma unroll
;     for (int o = 1; o < 64; o <<= 1)
; #pragma unroll
;         for (int i = 0; i < NR; ++i) { sna[i] += shfl_xor_l(sna[i], lane, o); ssg[i] += shfl_xor_l(ssg[i], lane, o); sme[i] += shfl_xor_l(sme[i], lane, o); }
; __device__ __forceinline__ void p5_unit(const Ptrs& P, LAS unsigned char* lds, int unit, int tid_in, int wave) {
;     ...
;     for (int hb = 0; hb < 2; ++hb) rescale_rows<4>(Y + ((size_t)tok0 + wave * 8 + hb * 4) * DM, (size_t)DM, g0, g1, lane);
.LBB0_236:
	s_or_b64 s[10:11], s[10:11], s[6:7]
	s_lshl_b64 s[10:11], s[10:11], 12
	v_lshl_add_u64 v[80:81], v[72:73], 0, s[10:11]
	v_add_co_u32_e32 v78, vcc, s71, v80
	s_movk_i32 s10, 0x2000
	s_nop 0
	v_addc_co_u32_e32 v79, vcc, 0, v81, vcc
	v_add_co_u32_e32 v76, vcc, s10, v80
	s_movk_i32 s10, 0x3000
	s_nop 0
	v_addc_co_u32_e32 v77, vcc, 0, v81, vcc
	v_add_co_u32_e32 v74, vcc, s10, v80
	global_load_dwordx4 v[82:85], v[80:81], off
	global_load_dwordx4 v[86:89], v[80:81], off offset:1024
	global_load_dwordx4 v[90:93], v[80:81], off offset:2048
	global_load_dwordx4 v[94:97], v[80:81], off offset:3072
	global_load_dwordx4 v[108:111], v[78:79], off offset:1024
	global_load_dwordx4 v[68:71], v[78:79], off offset:2048
	global_load_dwordx4 v[56:59], v[76:77], off
	global_load_dwordx4 v[60:63], v[76:77], off offset:1024
	global_load_dwordx4 v[52:55], v[76:77], off offset:2048
	global_load_dwordx4 v[48:51], v[76:77], off offset:3072
	v_addc_co_u32_e32 v75, vcc, 0, v81, vcc
	global_load_dwordx4 v[64:67], v[78:79], off offset:3072
	global_load_dwordx4 v[40:43], v[74:75], off
	global_load_dwordx4 v[44:47], v[74:75], off offset:1024
	global_load_dwordx4 v[36:39], v[74:75], off offset:2048
	global_load_dwordx4 v[112:115], v[76:77], off offset:-4096
	global_load_dwordx4 v[32:35], v[74:75], off offset:3072
	s_waitcnt vmcnt(14)
	v_and_b32_e32 v181, 0xffff0000, v86
	v_and_b32_e32 v180, 0xffff0000, v82
	v_and_b32_e32 v185, 0xffff0000, v87
	v_and_b32_e32 v184, 0xffff0000, v83
	v_lshlrev_b32_e32 v179, 16, v86
	v_lshlrev_b32_e32 v178, 16, v82
	v_lshlrev_b32_e32 v183, 16, v87
	v_lshlrev_b32_e32 v182, 16, v83
	v_lshlrev_b32_e32 v186, 16, v84
	v_and_b32_e32 v188, 0xffff0000, v84
	v_lshlrev_b32_e32 v190, 16, v85
	v_and_b32_e32 v192, 0xffff0000, v85
	v_pk_mul_f32 v[82:83], v[180:181], v[180:181]
	v_pk_mul_f32 v[84:85], v[184:185], v[184:185]
	v_and_b32_e32 v189, 0xffff0000, v88
	v_pk_fma_f32 v[82:83], v[178:179], v[178:179], v[82:83]
	v_pk_fma_f32 v[84:85], v[182:183], v[182:183], v[84:85]
	v_lshlrev_b32_e32 v187, 16, v88
	v_pk_add_f32 v[82:83], v[82:83], v[84:85]
	v_pk_mul_f32 v[84:85], v[188:189], v[188:189]
	v_and_b32_e32 v193, 0xffff0000, v89
	v_pk_fma_f32 v[84:85], v[186:187], v[186:187], v[84:85]
	v_lshlrev_b32_e32 v191, 16, v89
	v_pk_add_f32 v[82:83], v[84:85], v[82:83]
	v_pk_mul_f32 v[84:85], v[192:193], v[192:193]
	s_waitcnt vmcnt(13)
	v_and_b32_e32 v197, 0xffff0000, v91
	v_pk_fma_f32 v[84:85], v[190:191], v[190:191], v[84:85]
	v_and_b32_e32 v196, 0xffff0000, v90
	v_pk_add_f32 v[176:177], v[84:85], v[82:83]
	v_lshlrev_b32_e32 v195, 16, v91
	v_lshlrev_b32_e32 v194, 16, v90
	v_pk_mul_f32 v[82:83], v[196:197], v[196:197]
	v_and_b32_e32 v201, 0xffff0000, v93
	v_and_b32_e32 v200, 0xffff0000, v92
	v_pk_fma_f32 v[82:83], v[194:195], v[194:195], v[82:83]
	v_lshlrev_b32_e32 v199, 16, v93
	v_lshlrev_b32_e32 v198, 16, v92
	v_pk_mul_f32 v[84:85], v[200:201], v[200:201]
	v_pk_add_f32 v[82:83], v[82:83], v[82:83] op_sel:[0,1] op_sel_hi:[1,0]
	v_pk_fma_f32 v[210:211], v[198:199], v[198:199], v[84:85]
	s_waitcnt vmcnt(12)
	v_and_b32_e32 v101, 0xffff0000, v95
	v_pk_add_f32 v[208:209], v[210:211], v[82:83]
	v_pk_mov_b32 v[210:211], v[210:211], v[176:177] op_sel:[1,0]
	v_mov_b32_e32 v209, v177
	v_pk_add_f32 v[176:177], v[210:211], v[208:209]
	ds_bpermute_b32 v209, v144, v177
	ds_bpermute_b32 v208, v144, v176
	v_and_b32_e32 v100, 0xffff0000, v94
	v_lshlrev_b32_e32 v99, 16, v95
	v_lshlrev_b32_e32 v98, 16, v94
	v_pk_mul_f32 v[82:83], v[100:101], v[100:101]
	s_waitcnt lgkmcnt(0)
	v_pk_add_f32 v[176:177], v[176:177], v[208:209]
	ds_bpermute_b32 v209, v218, v177
	ds_bpermute_b32 v208, v218, v176
	v_and_b32_e32 v107, 0xffff0000, v97
	v_and_b32_e32 v106, 0xffff0000, v96
	v_pk_fma_f32 v[82:83], v[98:99], v[98:99], v[82:83]
	v_lshlrev_b32_e32 v103, 16, v97
	s_waitcnt lgkmcnt(0)
	v_pk_add_f32 v[176:177], v[176:177], v[208:209]
	ds_bpermute_b32 v209, v219, v177
	ds_bpermute_b32 v208, v219, v176
	v_lshlrev_b32_e32 v102, 16, v96
	v_pk_mul_f32 v[84:85], v[106:107], v[106:107]
	v_pk_add_f32 v[82:83], v[82:83], v[82:83] op_sel:[0,1] op_sel_hi:[1,0]
	v_pk_fma_f32 v[202:203], v[102:103], v[102:103], v[84:85]
	s_waitcnt lgkmcnt(0)
	v_pk_add_f32 v[176:177], v[176:177], v[208:209]
	s_waitcnt vmcnt(11)
	v_and_b32_e32 v85, 0xffff0000, v108
	s_waitcnt vmcnt(1)
	v_and_b32_e32 v84, 0xffff0000, v112
	v_and_b32_e32 v89, 0xffff0000, v109
	v_and_b32_e32 v88, 0xffff0000, v113
	ds_bpermute_b32 v209, v220, v177
	ds_bpermute_b32 v208, v220, v176
	v_pk_add_f32 v[204:205], v[202:203], v[82:83]
	v_lshlrev_b32_e32 v83, 16, v108
	v_lshlrev_b32_e32 v82, 16, v112
	v_lshlrev_b32_e32 v87, 16, v109
	v_lshlrev_b32_e32 v86, 16, v113
	v_pk_mul_f32 v[104:105], v[84:85], v[84:85]
	v_pk_mul_f32 v[108:109], v[88:89], v[88:89]
	v_and_b32_e32 v93, 0xffff0000, v110
	v_and_b32_e32 v92, 0xffff0000, v114
	v_pk_fma_f32 v[104:105], v[82:83], v[82:83], v[104:105]
	v_pk_fma_f32 v[108:109], v[86:87], v[86:87], v[108:109]
	v_lshlrev_b32_e32 v91, 16, v110
	v_lshlrev_b32_e32 v90, 16, v114
	v_pk_add_f32 v[104:105], v[104:105], v[108:109]
	v_pk_mul_f32 v[108:109], v[92:93], v[92:93]
	v_and_b32_e32 v97, 0xffff0000, v111
	v_and_b32_e32 v96, 0xffff0000, v115
	v_pk_fma_f32 v[108:109], v[90:91], v[90:91], v[108:109]
	v_lshlrev_b32_e32 v95, 16, v111
	v_lshlrev_b32_e32 v94, 16, v115
	v_pk_add_f32 v[104:105], v[108:109], v[104:105]
	v_pk_mul_f32 v[108:109], v[96:97], v[96:97]
	s_waitcnt lgkmcnt(0)
; __device__ __forceinline__ unsigned pk2(float lo, float hi) { unsigned r; asm("v_cvt_pk_bf16_f32 %0, %1, %2" : "=v"(r) : "v"(lo), "v"(hi)); return r; }
; __device__ __forceinline__ float bflo(unsigned u) { return __uint_as_float(u << 16); }
; __device__ __forceinline__ float bfhi(unsigned u) { return __uint_as_float(u & 0xffff0000u); }
; __device__ __forceinline__ float shfl_xor_l(float v, int lane, int mask) { return __int_as_float(__builtin_amdgcn_ds_bpermute((lane ^ mask) << 2, __float_as_int(v))); }
; template <int NR>
; __device__ __forceinline__ void rescale_rows(bf16_t* y, size_t stride, const f32x4 (&g0)[4], const f32x4 (&g1)[4], int lane) {
;     ...
;     float sna[NR], ssg[NR], sme[NR];
; #pragma unroll
;     for (int i = 0; i < NR; ++i) {
;         float ss[4];
; #pragma unroll
;         for (int j = 0; j < 4; ++j) { const u32x4 v = w[i][j];
;             const float a0 = bflo(v.x), a1 = bfhi(v.x), a2 = bflo(v.y), a3 = bfhi(v.y), a4 = bflo(v.z), a5 = bfhi(v.z), a6 = bflo(v.w), a7 = bfhi(v.w);
;             ss[j] = (a0 * a0 + a1 * a1) + (a2 * a2 + a3 * a3) + (a4 * a4 + a5 * a5) + (a6 * a6 + a7 * a7); }
;         sna[i] = ss[0] + ss[1]; ssg[i] = ss[2]; sme[i] = ss[3];
;     }
; #pragma unroll
;     for (int o = 1; o < 64; o <<= 1)
; #pragma unroll
;         for (int i = 0; i < NR; ++i) { sna[i] += shfl_xor_l(sna[i], lane, o); ssg[i] += shfl_xor_l(ssg[i], lane, o); sme[i] += shfl_xor_l(sme[i], lane, o); }
; #pragma unroll
;     for (int i = 0; i < NR; ++i) {
;         const float rna = rsqrtf(sna[i] * (1.0f / 1024) + EPS), rsg = rsqrtf(ssg[i] * (1.0f / 512) + EPS), rme = rsqrtf(sme[i] * (1.0f / 512) + EPS);
; #pragma unroll
;         for (int j = 0; j < 4; ++j) { const float r = j < 2 ? rna : j == 2 ? rsg : rme; const u32x4 v = w[i][j];
;             u32x4 o; o.x = pk2(bflo(v.x) * r * g0[j].x, bfhi(v.x) * r * g0[j].y); o.y = pk2(bflo(v.y) * r * g0[j].z, bfhi(v.y) * r * g0[j].w);
;             o.z = pk2(bflo(v.z) * r * g1[j].x, bfhi(v.z) * r * g1[j].y); o.w = pk2(bflo(v.w) * r * g1[j].z, bfhi(v.w) * r * g1[j].w);
;             *(u32x4*)(y + (size_t)i * stride + 512 * j + 8 * lane) = o; }
	v_pk_add_f32 v[176:177], v[176:177], v[208:209]
	v_pk_fma_f32 v[108:109], v[94:95], v[94:95], v[108:109]
	v_and_b32_e32 v111, 0xffff0000, v69
	v_and_b32_e32 v110, 0xffff0000, v68
	v_and_b32_e32 v119, 0xffff0000, v65
	v_and_b32_e32 v118, 0xffff0000, v64
	ds_bpermute_b32 v209, v221, v177
	ds_bpermute_b32 v208, v221, v176
	v_pk_add_f32 v[206:207], v[108:109], v[104:105]
	v_lshlrev_b32_e32 v109, 16, v69
	v_lshlrev_b32_e32 v108, 16, v68
	v_pk_mul_f32 v[68:69], v[110:111], v[110:111]
	v_and_b32_e32 v115, 0xffff0000, v71
	v_and_b32_e32 v114, 0xffff0000, v70
	v_lshlrev_b32_e32 v117, 16, v65
	v_lshlrev_b32_e32 v116, 16, v64
	v_pk_mul_f32 v[64:65], v[118:119], v[118:119]
	v_and_b32_e32 v123, 0xffff0000, v67
	v_and_b32_e32 v122, 0xffff0000, v66
	v_pk_fma_f32 v[150:151], v[108:109], v[108:109], v[68:69]
	v_lshlrev_b32_e32 v113, 16, v71
	v_lshlrev_b32_e32 v112, 16, v70
	v_pk_mul_f32 v[68:69], v[114:115], v[114:115]
	v_pk_fma_f32 v[158:159], v[116:117], v[116:117], v[64:65]
	v_lshlrev_b32_e32 v121, 16, v67
	v_lshlrev_b32_e32 v120, 16, v66
	v_pk_mul_f32 v[64:65], v[122:123], v[122:123]
	v_pk_fma_f32 v[156:157], v[112:113], v[112:113], v[68:69]
	v_pk_fma_f32 v[160:161], v[120:121], v[120:121], v[64:65]
	v_lshlrev_b32_e32 v65, 16, v60
	v_and_b32_e32 v67, 0xffff0000, v60
	v_and_b32_e32 v66, 0xffff0000, v56
	v_lshlrev_b32_e32 v69, 16, v61
	v_and_b32_e32 v61, 0xffff0000, v61
	v_and_b32_e32 v60, 0xffff0000, v57
	v_lshlrev_b32_e32 v64, 16, v56
	v_lshlrev_b32_e32 v68, 16, v57
	v_lshlrev_b32_e32 v57, 16, v62
	v_lshlrev_b32_e32 v56, 16, v58
	v_and_b32_e32 v71, 0xffff0000, v62
	v_and_b32_e32 v70, 0xffff0000, v58
	v_lshlrev_b32_e32 v104, 16, v59
	v_and_b32_e32 v62, 0xffff0000, v59
	v_pk_mul_f32 v[58:59], v[66:67], v[66:67]
	v_pk_mul_f32 v[124:125], v[60:61], v[60:61]
	v_pk_fma_f32 v[58:59], v[64:65], v[64:65], v[58:59]
	v_pk_fma_f32 v[124:125], v[68:69], v[68:69], v[124:125]
	s_waitcnt lgkmcnt(0)
	v_pk_add_f32 v[176:177], v[176:177], v[208:209]
	v_pk_add_f32 v[58:59], v[58:59], v[124:125]
	v_pk_mul_f32 v[124:125], v[70:71], v[70:71]
	ds_bpermute_b32 v209, v222, v177
	ds_bpermute_b32 v208, v222, v176
	v_lshlrev_b32_e32 v105, 16, v63
	v_and_b32_e32 v63, 0xffff0000, v63
	v_pk_fma_f32 v[124:125], v[56:57], v[56:57], v[124:125]
	v_and_b32_e32 v127, 0xffff0000, v49
	v_pk_add_f32 v[58:59], v[124:125], v[58:59]
	v_pk_mul_f32 v[124:125], v[62:63], v[62:63]
	v_and_b32_e32 v126, 0xffff0000, v48
	v_pk_fma_f32 v[124:125], v[104:105], v[104:105], v[124:125]
	v_and_b32_e32 v135, 0xffff0000, v51
	v_pk_add_f32 v[142:143], v[124:125], v[58:59]
	v_lshlrev_b32_e32 v125, 16, v49
	v_lshlrev_b32_e32 v124, 16, v48
	v_pk_mul_f32 v[48:49], v[126:127], v[126:127]
	v_and_b32_e32 v134, 0xffff0000, v50
	s_mov_b32 s10, 0x358637bd
	v_pk_fma_f32 v[48:49], v[124:125], v[124:125], v[48:49]
	v_lshlrev_b32_e32 v133, 16, v51
	v_lshlrev_b32_e32 v132, 16, v50
	v_pk_mul_f32 v[50:51], v[134:135], v[134:135]
	s_waitcnt lgkmcnt(0)
	v_pk_add_f32 v[208:209], v[176:177], v[208:209]
	v_mov_b64_e32 v[176:177], s[10:11]
	v_pk_add_f32 v[48:49], v[48:49], v[48:49] op_sel:[0,1] op_sel_hi:[1,0]
	v_pk_fma_f32 v[152:153], v[132:133], v[132:133], v[50:51]
	v_pk_fma_f32 v[208:209], v[208:209], s[24:25], v[176:177] op_sel_hi:[1,1,0]
	v_pk_add_f32 v[154:155], v[152:153], v[48:49]
	v_mul_f32_e32 v152, 0x4b800000, v209
	v_cmp_gt_f32_e64 s[38:39], s45, v209
	v_and_b32_e32 v131, 0xffff0000, v53
	v_and_b32_e32 v130, 0xffff0000, v52
	v_cndmask_b32_e64 v152, v209, v152, s[38:39]
	v_lshlrev_b32_e32 v129, 16, v53
	v_lshlrev_b32_e32 v128, 16, v52
	v_pk_mul_f32 v[52:53], v[130:131], v[130:131]
	v_and_b32_e32 v139, 0xffff0000, v55
	v_and_b32_e32 v138, 0xffff0000, v54
	v_rsq_f32_e32 v152, v152
	v_pk_fma_f32 v[52:53], v[128:129], v[128:129], v[52:53]
	v_lshlrev_b32_e32 v137, 16, v55
	v_lshlrev_b32_e32 v136, 16, v54
	v_pk_mul_f32 v[54:55], v[138:139], v[138:139]
	v_pk_add_f32 v[52:53], v[52:53], v[52:53] op_sel:[0,1] op_sel_hi:[1,0]
	v_pk_fma_f32 v[164:165], v[136:137], v[136:137], v[54:55]
	v_cmp_gt_f32_e32 vcc, s45, v208
	v_pk_add_f32 v[162:163], v[164:165], v[52:53]
	s_mov_b32 s10, s25
	v_mul_f32_e32 v163, 0x45800000, v152
	v_cndmask_b32_e64 v152, v152, v163, s[38:39]
	v_mul_f32_e32 v178, v152, v178
	v_mul_f32_e32 v163, 0x4b800000, v208
	v_mul_f32_e32 v178, v8, v178
	v_mul_f32_e32 v180, v152, v180
	v_cndmask_b32_e32 v163, v208, v163, vcc
	v_mul_f32_e32 v180, v9, v180
	v_cvt_pk_bf16_f32 v208, v178, v180
	v_mul_f32_e32 v178, v152, v182
	v_mul_f32_e32 v178, v10, v178
	v_mul_f32_e32 v180, v152, v184
	v_mul_f32_e32 v180, v11, v180
	v_cvt_pk_bf16_f32 v209, v178, v180
	v_mul_f32_e32 v178, v152, v186
	v_mul_f32_e32 v178, v16, v178
	v_mul_f32_e32 v180, v152, v188
	v_mul_f32_e32 v180, v17, v180
	v_cvt_pk_bf16_f32 v210, v178, v180
	v_mul_f32_e32 v178, v152, v190
	v_mul_f32_e32 v178, v18, v178
	v_mul_f32_e32 v180, v152, v192
	v_mul_f32_e32 v180, v19, v180
	v_cvt_pk_bf16_f32 v211, v178, v180
	v_mul_f32_e32 v178, v152, v179
	v_mul_f32_e32 v179, v152, v181
	v_mul_f32_e32 v178, v0, v178
	v_mul_f32_e32 v179, v1, v179
	v_rsq_f32_e32 v163, v163
	v_cvt_pk_bf16_f32 v178, v178, v179
	v_mul_f32_e32 v179, v152, v183
	v_mul_f32_e32 v180, v152, v185
	v_mul_f32_e32 v179, v2, v179
	v_mul_f32_e32 v180, v3, v180
	v_cvt_pk_bf16_f32 v179, v179, v180
	v_mul_f32_e32 v180, v152, v187
	v_mul_f32_e32 v181, v152, v189
	v_mul_f32_e32 v180, v4, v180
	v_mul_f32_e32 v181, v5, v181
	v_mul_f32_e32 v202, 0x45800000, v163
	v_cvt_pk_bf16_f32 v180, v180, v181
	v_mul_f32_e32 v181, v152, v191
	v_mul_f32_e32 v152, v152, v193
	v_cndmask_b32_e32 v163, v163, v202, vcc
	v_mul_f32_e32 v181, v6, v181
	v_mul_f32_e32 v152, v7, v152
	v_cvt_pk_bf16_f32 v181, v181, v152
	global_store_dwordx4 v[80:81], v[178:181], off offset:1024
	v_mul_f32_e32 v152, v163, v194
	v_mul_f32_e32 v152, v12, v152
	v_mul_f32_e32 v178, v163, v196
	v_mul_f32_e32 v178, v13, v178
	v_cvt_pk_bf16_f32 v178, v152, v178
	v_mul_f32_e32 v152, v163, v195
	v_mul_f32_e32 v179, v163, v197
	v_mul_f32_e32 v152, v14, v152
	v_mul_f32_e32 v179, v15, v179
	v_cvt_pk_bf16_f32 v179, v152, v179
	v_mul_f32_e32 v152, v163, v198
	v_mul_f32_e32 v180, v163, v200
	v_mul_f32_e32 v152, v24, v152
	v_mul_f32_e32 v180, v25, v180
	v_cvt_pk_bf16_f32 v180, v152, v180
	v_mul_f32_e32 v152, v163, v199
	v_mul_f32_e32 v163, v163, v201
	v_mul_f32_e32 v152, v26, v152
	v_mul_f32_e32 v163, v27, v163
	v_cvt_pk_bf16_f32 v181, v152, v163
	global_store_dwordx4 v[80:81], v[178:181], off offset:2048
	v_mov_b32_e32 v202, v206
	s_mov_b32 s11, s24
	v_pk_mov_b32 v[178:179], v[206:207], v[204:205] op_sel:[1,0]
	global_store_dwordx4 v[80:81], v[208:211], off
	v_pk_add_f32 v[178:179], v[202:203], v[178:179]
	ds_bpermute_b32 v181, v144, v179
	ds_bpermute_b32 v180, v144, v178
	v_lshlrev_b32_e32 v49, 16, v44
	v_and_b32_e32 v51, 0xffff0000, v44
	v_and_b32_e32 v50, 0xffff0000, v40
	v_lshlrev_b32_e32 v53, 16, v45
	s_waitcnt lgkmcnt(0)
; __device__ __forceinline__ unsigned pk2(float lo, float hi) { unsigned r; asm("v_cvt_pk_bf16_f32 %0, %1, %2" : "=v"(r) : "v"(lo), "v"(hi)); return r; }
; __device__ __forceinline__ float bflo(unsigned u) { return __uint_as_float(u << 16); }
; __device__ __forceinline__ float bfhi(unsigned u) { return __uint_as_float(u & 0xffff0000u); }
; __device__ __forceinline__ float shfl_xor_l(float v, int lane, int mask) { return __int_as_float(__builtin_amdgcn_ds_bpermute((lane ^ mask) << 2, __float_as_int(v))); }
; template <int NR>
; __device__ __forceinline__ void rescale_rows(bf16_t* y, size_t stride, const f32x4 (&g0)[4], const f32x4 (&g1)[4], int lane) {
;     ...
; #pragma unroll
;     for (int o = 1; o < 64; o <<= 1)
; #pragma unroll
;         for (int i = 0; i < NR; ++i) { sna[i] += shfl_xor_l(sna[i], lane, o); ssg[i] += shfl_xor_l(ssg[i], lane, o); sme[i] += shfl_xor_l(sme[i], lane, o); }
; #pragma unroll
;     for (int i = 0; i < NR; ++i) {
;         const float rna = rsqrtf(sna[i] * (1.0f / 1024) + EPS), rsg = rsqrtf(ssg[i] * (1.0f / 512) + EPS), rme = rsqrtf(sme[i] * (1.0f / 512) + EPS);
; #pragma unroll
;         for (int j = 0; j < 4; ++j) { const float r = j < 2 ? rna : j == 2 ? rsg : rme; const u32x4 v = w[i][j];
;             u32x4 o; o.x = pk2(bflo(v.x) * r * g0[j].x, bfhi(v.x) * r * g0[j].y); o.y = pk2(bflo(v.y) * r * g0[j].z, bfhi(v.y) * r * g0[j].w);
;             o.z = pk2(bflo(v.z) * r * g1[j].x, bfhi(v.z) * r * g1[j].y); o.w = pk2(bflo(v.w) * r * g1[j].z, bfhi(v.w) * r * g1[j].w);
;             *(u32x4*)(y + (size_t)i * stride + 512 * j + 8 * lane) = o; }
	v_pk_add_f32 v[178:179], v[178:179], v[180:181]
	ds_bpermute_b32 v181, v218, v179
	ds_bpermute_b32 v180, v218, v178
	v_and_b32_e32 v45, 0xffff0000, v45
	v_and_b32_e32 v44, 0xffff0000, v41
	v_lshlrev_b32_e32 v48, 16, v40
	v_lshlrev_b32_e32 v52, 16, v41
	s_waitcnt lgkmcnt(0)
	v_pk_add_f32 v[178:179], v[178:179], v[180:181]
	ds_bpermute_b32 v181, v219, v179
	ds_bpermute_b32 v180, v219, v178
	v_lshlrev_b32_e32 v41, 16, v46
	v_lshlrev_b32_e32 v40, 16, v42
	v_and_b32_e32 v55, 0xffff0000, v46
	v_and_b32_e32 v54, 0xffff0000, v42
	s_waitcnt lgkmcnt(0)
	v_pk_add_f32 v[178:179], v[178:179], v[180:181]
	ds_bpermute_b32 v181, v220, v179
	ds_bpermute_b32 v180, v220, v178
	v_lshlrev_b32_e32 v58, 16, v43
	v_and_b32_e32 v46, 0xffff0000, v43
	v_pk_mul_f32 v[42:43], v[50:51], v[50:51]
	v_pk_mul_f32 v[140:141], v[44:45], v[44:45]
	s_waitcnt lgkmcnt(0)
	v_pk_add_f32 v[178:179], v[178:179], v[180:181]
	ds_bpermute_b32 v181, v221, v179
	ds_bpermute_b32 v180, v221, v178
	v_pk_fma_f32 v[42:43], v[48:49], v[48:49], v[42:43]
	v_pk_fma_f32 v[140:141], v[52:53], v[52:53], v[140:141]
	v_lshlrev_b32_e32 v59, 16, v47
	v_pk_add_f32 v[42:43], v[42:43], v[140:141]
	s_waitcnt lgkmcnt(0)
	v_pk_add_f32 v[178:179], v[178:179], v[180:181]
	ds_bpermute_b32 v181, v222, v179
	ds_bpermute_b32 v180, v222, v178
	v_pk_mul_f32 v[140:141], v[54:55], v[54:55]
	v_and_b32_e32 v47, 0xffff0000, v47
	v_pk_fma_f32 v[140:141], v[40:41], v[40:41], v[140:141]
	s_waitcnt lgkmcnt(0)
	v_pk_add_f32 v[178:179], v[178:179], v[180:181]
	s_nop 0
	v_pk_fma_f32 v[178:179], v[178:179], s[10:11], v[176:177] op_sel_hi:[1,1,0]
	v_pk_add_f32 v[42:43], v[140:141], v[42:43]
	v_mul_f32_e32 v152, 0x4b800000, v179
	v_cmp_gt_f32_e64 s[38:39], s45, v179
	v_cmp_gt_f32_e32 vcc, s45, v178
	v_pk_mul_f32 v[140:141], v[46:47], v[46:47]
	v_cndmask_b32_e64 v152, v179, v152, s[38:39]
	v_rsq_f32_e32 v152, v152
	v_pk_fma_f32 v[140:141], v[58:59], v[58:59], v[140:141]
	v_mul_f32_e32 v163, 0x45800000, v152
	v_cndmask_b32_e64 v152, v152, v163, s[38:39]
	v_mul_f32_e32 v98, v152, v98
	v_mul_f32_e32 v100, v152, v100
	v_mul_f32_e32 v98, v20, v98
	v_mul_f32_e32 v100, v21, v100
	v_cvt_pk_bf16_f32 v98, v98, v100
	v_mul_f32_e32 v99, v152, v99
	v_mul_f32_e32 v100, v152, v101
	v_mul_f32_e32 v99, v22, v99
	v_mul_f32_e32 v100, v23, v100
	v_cvt_pk_bf16_f32 v99, v99, v100
	v_mul_f32_e32 v100, v152, v102
	v_mul_f32_e32 v101, v152, v106
	v_mul_f32_e32 v100, v28, v100
	v_mul_f32_e32 v101, v29, v101
	v_cvt_pk_bf16_f32 v100, v100, v101
	v_mul_f32_e32 v101, v152, v103
	v_mul_f32_e32 v101, v30, v101
	v_mul_f32_e32 v102, v152, v107
	v_mul_f32_e32 v102, v31, v102
	v_cvt_pk_bf16_f32 v101, v101, v102
	global_store_dwordx4 v[80:81], v[98:101], off offset:3072
	v_mul_f32_e32 v80, 0x4b800000, v178
	v_cndmask_b32_e32 v80, v178, v80, vcc
	v_rsq_f32_e32 v80, v80
	v_mov_b32_e32 v98, v160
	v_mov_b32_e32 v99, v156
	v_mov_b32_e32 v156, v161
	v_mul_f32_e32 v81, 0x45800000, v80
	v_cndmask_b32_e32 v102, v80, v81, vcc
	v_mov_b32_e32 v80, v158
	v_mov_b32_e32 v81, v150
	v_mov_b32_e32 v150, v159
	v_pk_add_f32 v[80:81], v[80:81], v[150:151]
	v_mov_b32_e32 v163, v143
	v_pk_add_f32 v[80:81], v[98:99], v[80:81]
	v_pk_add_f32 v[168:169], v[140:141], v[42:43]
	v_pk_add_f32 v[80:81], v[156:157], v[80:81]
	ds_bpermute_b32 v99, v144, v81
	ds_bpermute_b32 v98, v144, v80
	v_mov_b32_e32 v152, v168
	v_lshlrev_b32_e32 v43, 16, v37
	v_lshlrev_b32_e32 v42, 16, v36
	v_and_b32_e32 v37, 0xffff0000, v37
	s_waitcnt lgkmcnt(0)
	v_pk_add_f32 v[80:81], v[80:81], v[98:99]
	ds_bpermute_b32 v99, v218, v81
	ds_bpermute_b32 v98, v218, v80
	v_and_b32_e32 v36, 0xffff0000, v36
	v_pk_mul_f32 v[140:141], v[36:37], v[36:37]
	s_waitcnt lgkmcnt(0)
	v_pk_add_f32 v[80:81], v[80:81], v[98:99]
	ds_bpermute_b32 v99, v219, v81
	ds_bpermute_b32 v98, v219, v80
	v_pk_fma_f32 v[166:167], v[42:43], v[42:43], v[140:141]
	v_lshlrev_b32_e32 v141, 16, v39
	v_lshlrev_b32_e32 v140, 16, v38
	v_and_b32_e32 v39, 0xffff0000, v39
	s_waitcnt lgkmcnt(0)
	v_pk_add_f32 v[80:81], v[80:81], v[98:99]
	ds_bpermute_b32 v99, v220, v81
	ds_bpermute_b32 v98, v220, v80
	v_and_b32_e32 v38, 0xffff0000, v38
	v_pk_mul_f32 v[146:147], v[38:39], v[38:39]
	s_waitcnt lgkmcnt(0)
	v_pk_add_f32 v[80:81], v[80:81], v[98:99]
	ds_bpermute_b32 v99, v221, v81
	ds_bpermute_b32 v98, v221, v80
	v_pk_fma_f32 v[170:171], v[140:141], v[140:141], v[146:147]
	s_waitcnt vmcnt(4)
	v_lshlrev_b32_e32 v147, 16, v33
	v_lshlrev_b32_e32 v146, 16, v32
	v_and_b32_e32 v33, 0xffff0000, v33
	s_waitcnt lgkmcnt(0)
	v_pk_add_f32 v[80:81], v[80:81], v[98:99]
	ds_bpermute_b32 v99, v222, v81
	ds_bpermute_b32 v98, v222, v80
	v_and_b32_e32 v32, 0xffff0000, v32
	v_pk_mul_f32 v[148:149], v[32:33], v[32:33]
	s_waitcnt lgkmcnt(0)
; __device__ __forceinline__ unsigned pk2(float lo, float hi) { unsigned r; asm("v_cvt_pk_bf16_f32 %0, %1, %2" : "=v"(r) : "v"(lo), "v"(hi)); return r; }
; __device__ __forceinline__ float bflo(unsigned u) { return __uint_as_float(u << 16); }
; __device__ __forceinline__ float bfhi(unsigned u) { return __uint_as_float(u & 0xffff0000u); }
; __device__ __forceinline__ float shfl_xor_l(float v, int lane, int mask) { return __int_as_float(__builtin_amdgcn_ds_bpermute((lane ^ mask) << 2, __float_as_int(v))); }
; template <int NR>
; __device__ __forceinline__ void rescale_rows(bf16_t* y, size_t stride, const f32x4 (&g0)[4], const f32x4 (&g1)[4], int lane) {
;     ...
; #pragma unroll
;     for (int o = 1; o < 64; o <<= 1)
; #pragma unroll
;         for (int i = 0; i < NR; ++i) { sna[i] += shfl_xor_l(sna[i], lane, o); ssg[i] += shfl_xor_l(ssg[i], lane, o); sme[i] += shfl_xor_l(sme[i], lane, o); }
; #pragma unroll
;     for (int i = 0; i < NR; ++i) {
;         const float rna = rsqrtf(sna[i] * (1.0f / 1024) + EPS), rsg = rsqrtf(ssg[i] * (1.0f / 512) + EPS), rme = rsqrtf(sme[i] * (1.0f / 512) + EPS);
; #pragma unroll
;         for (int j = 0; j < 4; ++j) { const float r = j < 2 ? rna : j == 2 ? rsg : rme; const u32x4 v = w[i][j];
;             u32x4 o; o.x = pk2(bflo(v.x) * r * g0[j].x, bfhi(v.x) * r * g0[j].y); o.y = pk2(bflo(v.y) * r * g0[j].z, bfhi(v.y) * r * g0[j].w);
;             o.z = pk2(bflo(v.z) * r * g1[j].x, bfhi(v.z) * r * g1[j].y); o.w = pk2(bflo(v.w) * r * g1[j].z, bfhi(v.w) * r * g1[j].w);
;             *(u32x4*)(y + (size_t)i * stride + 512 * j + 8 * lane) = o; }
	v_pk_add_f32 v[80:81], v[80:81], v[98:99]
	s_nop 0
	v_pk_fma_f32 v[80:81], v[80:81], s[24:25], v[176:177] op_sel_hi:[1,0,0]
	v_pk_fma_f32 v[172:173], v[146:147], v[146:147], v[148:149]
	v_mul_f32_e32 v98, 0x4b800000, v81
	v_cmp_gt_f32_e64 s[38:39], s45, v81
	v_cmp_gt_f32_e32 vcc, s45, v80
	v_lshlrev_b32_e32 v149, 16, v35
	v_cndmask_b32_e64 v81, v81, v98, s[38:39]
	v_rsq_f32_e32 v81, v81
	v_lshlrev_b32_e32 v148, 16, v34
	v_and_b32_e32 v35, 0xffff0000, v35
	v_and_b32_e32 v34, 0xffff0000, v34
	v_mul_f32_e32 v98, 0x45800000, v81
	v_cndmask_b32_e64 v103, v81, v98, s[38:39]
	v_mul_f32_e32 v81, 0x4b800000, v80
	v_cndmask_b32_e32 v80, v80, v81, vcc
	v_rsq_f32_e32 v80, v80
	v_pk_mul_f32 v[174:175], v[34:35], v[34:35]
	v_mul_f32_e32 v81, 0x45800000, v80
	v_cndmask_b32_e32 v106, v80, v81, vcc
	v_mul_f32_e32 v80, v102, v82
	v_mul_f32_e32 v81, v102, v84
	v_mul_f32_e32 v80, v8, v80
	v_mul_f32_e32 v81, v9, v81
	v_cvt_pk_bf16_f32 v98, v80, v81
	v_mul_f32_e32 v80, v102, v86
	v_mul_f32_e32 v81, v102, v88
	v_mul_f32_e32 v80, v10, v80
	v_mul_f32_e32 v81, v11, v81
	v_cvt_pk_bf16_f32 v99, v80, v81
	v_mul_f32_e32 v80, v102, v90
	v_mul_f32_e32 v81, v102, v92
	v_mul_f32_e32 v80, v16, v80
	v_mul_f32_e32 v81, v17, v81
	v_cvt_pk_bf16_f32 v100, v80, v81
	v_mul_f32_e32 v80, v102, v94
	v_mul_f32_e32 v81, v102, v96
	v_mul_f32_e32 v80, v18, v80
	v_mul_f32_e32 v81, v19, v81
	v_cvt_pk_bf16_f32 v101, v80, v81
	v_mul_f32_e32 v80, v102, v83
	v_mul_f32_e32 v81, v102, v85
	v_mul_f32_e32 v80, v0, v80
	v_mul_f32_e32 v81, v1, v81
	v_cvt_pk_bf16_f32 v80, v80, v81
	v_mul_f32_e32 v81, v102, v87
	v_mul_f32_e32 v82, v102, v89
	v_mul_f32_e32 v81, v2, v81
	v_mul_f32_e32 v82, v3, v82
	v_cvt_pk_bf16_f32 v81, v81, v82
	v_mul_f32_e32 v82, v102, v91
	v_mul_f32_e32 v83, v102, v93
	v_mul_f32_e32 v82, v4, v82
	v_mul_f32_e32 v83, v5, v83
	v_cvt_pk_bf16_f32 v82, v82, v83
	v_mul_f32_e32 v83, v102, v95
	v_mul_f32_e32 v83, v6, v83
	v_mul_f32_e32 v84, v102, v97
	v_mul_f32_e32 v84, v7, v84
	v_cvt_pk_bf16_f32 v83, v83, v84
	global_store_dwordx4 v[78:79], v[80:83], off offset:1024
	v_mul_f32_e32 v84, v103, v115
	v_mul_f32_e32 v84, v27, v84
	v_mul_f32_e32 v80, v103, v108
	v_mul_f32_e32 v81, v103, v110
	v_mul_f32_e32 v80, v12, v80
	v_mul_f32_e32 v81, v13, v81
	v_cvt_pk_bf16_f32 v80, v80, v81
	v_mul_f32_e32 v81, v103, v109
	v_mul_f32_e32 v82, v103, v111
	v_mul_f32_e32 v81, v14, v81
	v_mul_f32_e32 v82, v15, v82
	v_cvt_pk_bf16_f32 v81, v81, v82
	v_mul_f32_e32 v82, v103, v112
	v_mul_f32_e32 v83, v103, v114
	v_mul_f32_e32 v82, v24, v82
	v_mul_f32_e32 v83, v25, v83
	v_cvt_pk_bf16_f32 v82, v82, v83
	v_mul_f32_e32 v83, v103, v113
	v_mul_f32_e32 v83, v26, v83
	v_cvt_pk_bf16_f32 v83, v83, v84
	global_store_dwordx4 v[78:79], v[80:83], off offset:2048
	v_mul_f32_e32 v84, v106, v123
	v_mul_f32_e32 v84, v31, v84
	v_mul_f32_e32 v80, v106, v116
	v_mul_f32_e32 v81, v106, v118
	v_mul_f32_e32 v80, v20, v80
	v_mul_f32_e32 v81, v21, v81
	v_cvt_pk_bf16_f32 v80, v80, v81
	v_mul_f32_e32 v81, v106, v117
	v_mul_f32_e32 v82, v106, v119
	v_mul_f32_e32 v81, v22, v81
	v_mul_f32_e32 v82, v23, v82
	v_cvt_pk_bf16_f32 v81, v81, v82
	v_mul_f32_e32 v82, v106, v120
	v_mul_f32_e32 v83, v106, v122
	v_mul_f32_e32 v82, v28, v82
	v_mul_f32_e32 v83, v29, v83
	v_cvt_pk_bf16_f32 v82, v82, v83
	v_mul_f32_e32 v83, v106, v121
	v_mul_f32_e32 v83, v30, v83
	v_cvt_pk_bf16_f32 v83, v83, v84
	global_store_dwordx4 v[78:79], v[80:83], off offset:3072
	v_pk_mov_b32 v[78:79], v[164:165], v[142:143] op_sel:[1,0]
	v_pk_fma_f32 v[174:175], v[148:149], v[148:149], v[174:175]
	v_pk_add_f32 v[78:79], v[78:79], v[162:163]
	ds_bpermute_b32 v81, v144, v79
	ds_bpermute_b32 v80, v144, v78
	global_store_dwordx4 v[76:77], v[98:101], off offset:-4096
	s_waitcnt lgkmcnt(0)
	v_pk_add_f32 v[78:79], v[78:79], v[80:81]
	ds_bpermute_b32 v81, v218, v79
	ds_bpermute_b32 v80, v218, v78
	s_waitcnt lgkmcnt(0)
	v_pk_add_f32 v[78:79], v[78:79], v[80:81]
	ds_bpermute_b32 v81, v219, v79
	ds_bpermute_b32 v80, v219, v78
	s_waitcnt lgkmcnt(0)
	v_pk_add_f32 v[78:79], v[78:79], v[80:81]
	ds_bpermute_b32 v81, v220, v79
	ds_bpermute_b32 v80, v220, v78
	s_waitcnt lgkmcnt(0)
	v_pk_add_f32 v[78:79], v[78:79], v[80:81]
	ds_bpermute_b32 v81, v221, v79
	ds_bpermute_b32 v80, v221, v78
	s_waitcnt lgkmcnt(0)
	v_pk_add_f32 v[78:79], v[78:79], v[80:81]
	ds_bpermute_b32 v81, v222, v79
	ds_bpermute_b32 v80, v222, v78
	s_waitcnt lgkmcnt(0)
; __device__ __forceinline__ unsigned pk2(float lo, float hi) { unsigned r; asm("v_cvt_pk_bf16_f32 %0, %1, %2" : "=v"(r) : "v"(lo), "v"(hi)); return r; }
; __device__ __forceinline__ float bflo(unsigned u) { return __uint_as_float(u << 16); }
; __device__ __forceinline__ float bfhi(unsigned u) { return __uint_as_float(u & 0xffff0000u); }
; __device__ __forceinline__ float shfl_xor_l(float v, int lane, int mask) { return __int_as_float(__builtin_amdgcn_ds_bpermute((lane ^ mask) << 2, __float_as_int(v))); }
; template <int NR>
; __device__ __forceinline__ void rescale_rows(bf16_t* y, size_t stride, const f32x4 (&g0)[4], const f32x4 (&g1)[4], int lane) {
;     ...
; #pragma unroll
;     for (int o = 1; o < 64; o <<= 1)
; #pragma unroll
;         for (int i = 0; i < NR; ++i) { sna[i] += shfl_xor_l(sna[i], lane, o); ssg[i] += shfl_xor_l(ssg[i], lane, o); sme[i] += shfl_xor_l(sme[i], lane, o); }
; #pragma unroll
;     for (int i = 0; i < NR; ++i) {
;         const float rna = rsqrtf(sna[i] * (1.0f / 1024) + EPS), rsg = rsqrtf(ssg[i] * (1.0f / 512) + EPS), rme = rsqrtf(sme[i] * (1.0f / 512) + EPS);
; #pragma unroll
;         for (int j = 0; j < 4; ++j) { const float r = j < 2 ? rna : j == 2 ? rsg : rme; const u32x4 v = w[i][j];
;             u32x4 o; o.x = pk2(bflo(v.x) * r * g0[j].x, bfhi(v.x) * r * g0[j].y); o.y = pk2(bflo(v.y) * r * g0[j].z, bfhi(v.y) * r * g0[j].w);
;             o.z = pk2(bflo(v.z) * r * g1[j].x, bfhi(v.z) * r * g1[j].y); o.w = pk2(bflo(v.w) * r * g1[j].z, bfhi(v.w) * r * g1[j].w);
;             *(u32x4*)(y + (size_t)i * stride + 512 * j + 8 * lane) = o; }
	v_pk_add_f32 v[78:79], v[78:79], v[80:81]
	s_nop 0
	v_pk_fma_f32 v[78:79], v[78:79], s[24:25], v[176:177] op_sel_hi:[1,1,0]
	s_nop 0
	v_mul_f32_e32 v80, 0x4b800000, v79
	v_cmp_gt_f32_e64 s[38:39], s45, v79
	v_cmp_gt_f32_e32 vcc, s45, v78
	s_nop 0
	v_cndmask_b32_e64 v79, v79, v80, s[38:39]
	v_rsq_f32_e32 v79, v79
	s_nop 0
	v_mul_f32_e32 v80, 0x45800000, v79
	v_cndmask_b32_e64 v82, v79, v80, s[38:39]
	v_mul_f32_e32 v79, 0x4b800000, v78
	v_cndmask_b32_e32 v78, v78, v79, vcc
	v_rsq_f32_e32 v78, v78
	v_mul_f32_e32 v64, v82, v64
	v_mul_f32_e32 v64, v8, v64
	v_mul_f32_e32 v66, v82, v66
	v_mul_f32_e32 v79, 0x45800000, v78
	v_mul_f32_e32 v60, v82, v60
	v_cndmask_b32_e32 v83, v78, v79, vcc
	v_mul_f32_e32 v66, v9, v66
	v_cvt_pk_bf16_f32 v78, v64, v66
	v_mul_f32_e32 v64, v82, v68
	v_mul_f32_e32 v60, v11, v60
	v_mul_f32_e32 v64, v10, v64
	v_cvt_pk_bf16_f32 v79, v64, v60
	v_mul_f32_e32 v56, v82, v56
	v_mul_f32_e32 v60, v82, v70
	v_mul_f32_e32 v56, v16, v56
	v_mul_f32_e32 v60, v17, v60
	v_cvt_pk_bf16_f32 v80, v56, v60
	v_mul_f32_e32 v56, v82, v104
	v_mul_f32_e32 v60, v82, v62
	v_mul_f32_e32 v56, v18, v56
	v_mul_f32_e32 v60, v19, v60
	v_cvt_pk_bf16_f32 v81, v56, v60
	v_mul_f32_e32 v56, v82, v65
	v_mul_f32_e32 v60, v82, v67
	v_mul_f32_e32 v56, v0, v56
	v_mul_f32_e32 v60, v1, v60
	v_cvt_pk_bf16_f32 v60, v56, v60
	v_mul_f32_e32 v56, v82, v69
	v_mul_f32_e32 v61, v82, v61
	v_mul_f32_e32 v56, v2, v56
	v_mul_f32_e32 v61, v3, v61
	v_cvt_pk_bf16_f32 v61, v56, v61
	v_mul_f32_e32 v56, v82, v57
	v_mul_f32_e32 v57, v82, v71
	v_mul_f32_e32 v56, v4, v56
	v_mul_f32_e32 v57, v5, v57
	v_cvt_pk_bf16_f32 v62, v56, v57
	v_mul_f32_e32 v56, v82, v105
	v_mul_f32_e32 v57, v82, v63
	v_mul_f32_e32 v56, v6, v56
	v_mul_f32_e32 v57, v7, v57
	v_cvt_pk_bf16_f32 v63, v56, v57
	v_mul_f32_e32 v56, v83, v128
	v_mul_f32_e32 v57, v83, v130
	v_mul_f32_e32 v56, v12, v56
	v_mul_f32_e32 v57, v13, v57
	global_store_dwordx4 v[76:77], v[60:63], off offset:1024
	global_store_dwordx4 v[76:77], v[78:81], off
	s_nop 0
	v_cvt_pk_bf16_f32 v60, v56, v57
	v_mul_f32_e32 v56, v83, v129
	v_mul_f32_e32 v57, v83, v131
	v_mul_f32_e32 v56, v14, v56
	v_mul_f32_e32 v57, v15, v57
	v_cvt_pk_bf16_f32 v61, v56, v57
	v_mul_f32_e32 v56, v83, v136
	v_mul_f32_e32 v57, v83, v138
	v_mul_f32_e32 v56, v24, v56
	v_mul_f32_e32 v57, v25, v57
	v_cvt_pk_bf16_f32 v62, v56, v57
	v_mul_f32_e32 v56, v83, v137
	v_mul_f32_e32 v57, v83, v139
	v_mul_f32_e32 v56, v26, v56
	v_mul_f32_e32 v57, v27, v57
	v_cvt_pk_bf16_f32 v63, v56, v57
	v_pk_mov_b32 v[56:57], v[168:169], v[154:155] op_sel:[1,0]
	global_store_dwordx4 v[76:77], v[60:63], off offset:2048
	v_pk_add_f32 v[56:57], v[152:153], v[56:57]
	ds_bpermute_b32 v61, v144, v57
	ds_bpermute_b32 v60, v144, v56
	s_waitcnt lgkmcnt(0)
	v_pk_add_f32 v[56:57], v[56:57], v[60:61]
	ds_bpermute_b32 v61, v218, v57
	ds_bpermute_b32 v60, v218, v56
	s_waitcnt lgkmcnt(0)
	v_pk_add_f32 v[56:57], v[56:57], v[60:61]
	ds_bpermute_b32 v61, v219, v57
	ds_bpermute_b32 v60, v219, v56
	s_waitcnt lgkmcnt(0)
	v_pk_add_f32 v[56:57], v[56:57], v[60:61]
	ds_bpermute_b32 v61, v220, v57
	ds_bpermute_b32 v60, v220, v56
	s_waitcnt lgkmcnt(0)
	v_pk_add_f32 v[56:57], v[56:57], v[60:61]
	ds_bpermute_b32 v61, v221, v57
	ds_bpermute_b32 v60, v221, v56
	s_waitcnt lgkmcnt(0)
	v_pk_add_f32 v[56:57], v[56:57], v[60:61]
	ds_bpermute_b32 v61, v222, v57
	ds_bpermute_b32 v60, v222, v56
	s_waitcnt lgkmcnt(0)
	v_pk_add_f32 v[56:57], v[56:57], v[60:61]
	s_nop 0
	v_pk_fma_f32 v[56:57], v[56:57], s[10:11], v[176:177] op_sel_hi:[1,1,0]
	s_mov_b64 s[10:11], 4
	v_mul_f32_e32 v60, 0x4b800000, v57
	v_cmp_gt_f32_e64 s[38:39], s45, v57
	v_cmp_gt_f32_e32 vcc, s45, v56
	s_nop 0
	v_cndmask_b32_e64 v57, v57, v60, s[38:39]
	v_rsq_f32_e32 v57, v57
	s_nop 0
	v_mul_f32_e32 v60, 0x45800000, v57
	v_cndmask_b32_e64 v57, v57, v60, s[38:39]
	v_mul_f32_e32 v60, v57, v124
	v_mul_f32_e32 v61, v57, v126
	v_mul_f32_e32 v60, v20, v60
	v_mul_f32_e32 v61, v21, v61
	v_cvt_pk_bf16_f32 v60, v60, v61
	v_mul_f32_e32 v61, v57, v125
	v_mul_f32_e32 v62, v57, v127
	v_mul_f32_e32 v61, v22, v61
	v_mul_f32_e32 v62, v23, v62
	v_cvt_pk_bf16_f32 v61, v61, v62
	v_mul_f32_e32 v62, v57, v132
	v_mul_f32_e32 v63, v57, v134
	v_mul_f32_e32 v62, v28, v62
	v_mul_f32_e32 v63, v29, v63
	v_cvt_pk_bf16_f32 v62, v62, v63
	v_mul_f32_e32 v63, v57, v133
	v_mul_f32_e32 v57, v57, v135
	v_mul_f32_e32 v63, v30, v63
	v_mul_f32_e32 v57, v31, v57
	v_cvt_pk_bf16_f32 v63, v63, v57
	v_mul_f32_e32 v57, 0x4b800000, v56
	v_cndmask_b32_e32 v56, v56, v57, vcc
	v_rsq_f32_e32 v56, v56
	global_store_dwordx4 v[76:77], v[60:63], off offset:3072
	v_mul_f32_e32 v57, 0x45800000, v56
	v_cndmask_b32_e32 v64, v56, v57, vcc
	v_mov_b32_e32 v56, v172
	v_mov_b32_e32 v57, v166
	v_mov_b32_e32 v166, v173
	v_pk_add_f32 v[56:57], v[56:57], v[166:167]
	v_mov_b32_e32 v60, v174
	v_mov_b32_e32 v61, v170
	v_pk_add_f32 v[56:57], v[60:61], v[56:57]
	v_mov_b32_e32 v170, v175
	v_pk_add_f32 v[56:57], v[170:171], v[56:57]
	ds_bpermute_b32 v61, v144, v57
	ds_bpermute_b32 v60, v144, v56
	v_mul_f32_e32 v48, v64, v48
	v_mul_f32_e32 v48, v8, v48
	v_mul_f32_e32 v50, v64, v50
	v_mul_f32_e32 v44, v64, v44
	s_waitcnt lgkmcnt(0)
; __device__ __forceinline__ unsigned pk2(float lo, float hi) { unsigned r; asm("v_cvt_pk_bf16_f32 %0, %1, %2" : "=v"(r) : "v"(lo), "v"(hi)); return r; }
; __device__ __forceinline__ float bflo(unsigned u) { return __uint_as_float(u << 16); }
; __device__ __forceinline__ float bfhi(unsigned u) { return __uint_as_float(u & 0xffff0000u); }
; template <int NR>
; __device__ __forceinline__ void rescale_rows(bf16_t* y, size_t stride, const f32x4 (&g0)[4], const f32x4 (&g1)[4], int lane) {
;     ...
;     for (int i = 0; i < NR; ++i) {
;         const float rna = rsqrtf(sna[i] * (1.0f / 1024) + EPS), rsg = rsqrtf(ssg[i] * (1.0f / 512) + EPS), rme = rsqrtf(sme[i] * (1.0f / 512) + EPS);
; #pragma unroll
;         for (int j = 0; j < 4; ++j) { const float r = j < 2 ? rna : j == 2 ? rsg : rme; const u32x4 v = w[i][j];
;             u32x4 o; o.x = pk2(bflo(v.x) * r * g0[j].x, bfhi(v.x) * r * g0[j].y); o.y = pk2(bflo(v.y) * r * g0[j].z, bfhi(v.y) * r * g0[j].w);
;             o.z = pk2(bflo(v.z) * r * g1[j].x, bfhi(v.z) * r * g1[j].y); o.w = pk2(bflo(v.w) * r * g1[j].z, bfhi(v.w) * r * g1[j].w);
;             *(u32x4*)(y + (size_t)i * stride + 512 * j + 8 * lane) = o; }
;     }
; }
; __global__ void __launch_bounds__(512, 2) fwd_kernel(Args a) {
;     ...
;             for (int u = bid; u < 256; u += G) p5_unit(P, lds, (G == 256) ? ((u & 7) * 32 + (u >> 3)) : u, tid, wave);
	v_pk_add_f32 v[56:57], v[56:57], v[60:61]
	ds_bpermute_b32 v61, v218, v57
	ds_bpermute_b32 v60, v218, v56
	v_mul_f32_e32 v50, v9, v50
	v_mul_f32_e32 v44, v11, v44
	v_mul_f32_e32 v40, v64, v40
	v_mul_f32_e32 v40, v16, v40
	s_waitcnt lgkmcnt(0)
	v_pk_add_f32 v[56:57], v[56:57], v[60:61]
	ds_bpermute_b32 v61, v219, v57
	ds_bpermute_b32 v60, v219, v56
	v_mul_f32_e32 v45, v64, v45
	v_mul_f32_e32 v45, v3, v45
	s_waitcnt lgkmcnt(0)
	v_pk_add_f32 v[56:57], v[56:57], v[60:61]
	ds_bpermute_b32 v61, v220, v57
	ds_bpermute_b32 v60, v220, v56
	s_waitcnt lgkmcnt(0)
	v_pk_add_f32 v[56:57], v[56:57], v[60:61]
	ds_bpermute_b32 v61, v221, v57
	ds_bpermute_b32 v60, v221, v56
	s_waitcnt lgkmcnt(0)
	v_pk_add_f32 v[56:57], v[56:57], v[60:61]
	ds_bpermute_b32 v61, v222, v57
	ds_bpermute_b32 v60, v222, v56
	s_waitcnt lgkmcnt(0)
	v_pk_add_f32 v[56:57], v[56:57], v[60:61]
	s_nop 0
	v_pk_fma_f32 v[56:57], v[56:57], s[24:25], v[176:177] op_sel_hi:[1,0,0]
	s_nop 0
	v_mul_f32_e32 v60, 0x4b800000, v57
	v_cmp_gt_f32_e64 s[38:39], s45, v57
	v_cmp_gt_f32_e32 vcc, s45, v56
	s_nop 0
	v_cndmask_b32_e64 v57, v57, v60, s[38:39]
	v_rsq_f32_e32 v57, v57
	s_nop 0
	v_mul_f32_e32 v60, 0x45800000, v57
	v_cndmask_b32_e64 v57, v57, v60, s[38:39]
	v_mul_f32_e32 v60, 0x4b800000, v56
	v_cndmask_b32_e32 v56, v56, v60, vcc
	v_rsq_f32_e32 v56, v56
	v_mul_f32_e32 v36, v57, v36
	v_mul_f32_e32 v36, v13, v36
	v_mul_f32_e32 v37, v57, v37
	v_mul_f32_e32 v60, 0x45800000, v56
	v_cndmask_b32_e32 v56, v56, v60, vcc
	v_cvt_pk_bf16_f32 v60, v48, v50
	v_mul_f32_e32 v48, v64, v52
	v_mul_f32_e32 v48, v10, v48
	v_cvt_pk_bf16_f32 v61, v48, v44
	v_mul_f32_e32 v44, v64, v54
	v_mul_f32_e32 v44, v17, v44
	v_cvt_pk_bf16_f32 v62, v40, v44
	v_mul_f32_e32 v40, v64, v58
	v_mul_f32_e32 v44, v64, v46
	v_mul_f32_e32 v40, v18, v40
	v_mul_f32_e32 v44, v19, v44
	v_cvt_pk_bf16_f32 v63, v40, v44
	v_mul_f32_e32 v40, v64, v49
	v_mul_f32_e32 v44, v64, v51
	v_mul_f32_e32 v40, v0, v40
	v_mul_f32_e32 v44, v1, v44
	v_cvt_pk_bf16_f32 v44, v40, v44
	v_mul_f32_e32 v40, v64, v53
	v_mul_f32_e32 v40, v2, v40
	v_cvt_pk_bf16_f32 v45, v40, v45
	v_mul_f32_e32 v40, v64, v41
	v_mul_f32_e32 v40, v4, v40
	v_mul_f32_e32 v41, v64, v55
	v_mul_f32_e32 v41, v5, v41
	v_cvt_pk_bf16_f32 v46, v40, v41
	v_mul_f32_e32 v40, v64, v59
	v_mul_f32_e32 v40, v6, v40
	v_mul_f32_e32 v41, v64, v47
	v_mul_f32_e32 v41, v7, v41
	v_cvt_pk_bf16_f32 v47, v40, v41
	v_mul_f32_e32 v40, v57, v42
	v_mul_f32_e32 v40, v12, v40
	v_cvt_pk_bf16_f32 v36, v40, v36
	v_mul_f32_e32 v40, v57, v43
	v_mul_f32_e32 v40, v14, v40
	v_mul_f32_e32 v37, v15, v37
	v_cvt_pk_bf16_f32 v37, v40, v37
	v_mul_f32_e32 v40, v57, v140
	v_mul_f32_e32 v38, v57, v38
	v_mul_f32_e32 v40, v24, v40
	v_mul_f32_e32 v38, v25, v38
	v_mul_f32_e32 v39, v57, v39
	v_cvt_pk_bf16_f32 v38, v40, v38
	v_mul_f32_e32 v40, v57, v141
	v_mul_f32_e32 v39, v27, v39
	v_mul_f32_e32 v40, v26, v40
	v_cvt_pk_bf16_f32 v39, v40, v39
	global_store_dwordx4 v[74:75], v[36:39], off offset:2048
	v_mul_f32_e32 v32, v56, v32
	v_mul_f32_e32 v32, v21, v32
	v_mul_f32_e32 v36, v56, v146
	v_mul_f32_e32 v36, v20, v36
	v_cvt_pk_bf16_f32 v32, v36, v32
	v_mul_f32_e32 v36, v56, v147
	v_mul_f32_e32 v33, v56, v33
	v_mul_f32_e32 v36, v22, v36
	v_mul_f32_e32 v33, v23, v33
	v_cvt_pk_bf16_f32 v33, v36, v33
	v_mul_f32_e32 v36, v56, v148
	v_mul_f32_e32 v34, v56, v34
	v_mul_f32_e32 v36, v28, v36
	v_mul_f32_e32 v34, v29, v34
	v_mul_f32_e32 v35, v56, v35
	v_cvt_pk_bf16_f32 v34, v36, v34
	v_mul_f32_e32 v36, v56, v149
	v_mul_f32_e32 v35, v31, v35
	s_and_b64 vcc, exec, s[8:9]
	s_mov_b64 s[8:9], 0
	global_store_dwordx4 v[74:75], v[60:63], off
	global_store_dwordx4 v[74:75], v[44:47], off offset:1024
	v_mul_f32_e32 v36, v30, v36
	v_cvt_pk_bf16_f32 v35, v36, v35
	global_store_dwordx4 v[74:75], v[32:35], off offset:3072
	s_cbranch_vccnz .LBB0_236
	s_setprio 0
	s_add_i32 s12, s12, s70
	s_cmpk_gt_i32 s12, 0xff
	s_cbranch_scc0 .LBB0_201
